# out-proj layer-0 epilogue: residual loads/stores widened to 16 B per lane via v_permlane16_swap regrouping, loads up front with counted waits
# speedup vs baseline: 1.0354x; 1.0022x over previous
; __device__ __forceinline__ unsigned cvt_pk_bf16(float lo, float hi) { unsigned r; asm volatile("v_cvt_pk_bf16_f32 %0, %1, %2" : "=v"(r) : "v"(lo), "v"(hi)); return r; }
;     __device__ __forceinline__ void operator()(const f32x4 (&acc)[2][2][4][2], const Unit& u, int wr, int wc, int fr, int fq) const {
;         typedef unsigned u32x2 __attribute__((ext_vector_type(2)));
;         const int col0 = u.pn * BM + wc * 32 + 4 * fq;
; #pragma unroll
;         for (int ai = 0; ai < 2; ++ai)
; #pragma unroll
;             for (int m = 0; m < 4; ++m) {
;                 const int row = u.pm * BM + ai * HALF + wr * 64 + m * 16 + fr;
;                 const size_t off = (size_t)row * 1024 + col0;
;                 float ss = 0.f;
; #pragma unroll
;                 for (int bj = 0; bj < 2; ++bj)
; #pragma unroll
;                     for (int n = 0; n < 2; ++n) {
;                         f32x4 bs;
;                         { const u32x2 hb = *(const u32x2*)(baseh + off + bj * HALF + n * 16); bs = (f32x4){__uint_as_float(hb.x << 16), __uint_as_float(hb.x & 0xffff0000u), __uint_as_float(hb.y << 16), __uint_as_float(hb.y & 0xffff0000u)}; }
;                         const f32x4 o = bs + acc[ai][bj][m][n];
;                         if (NEXT) { ss += (o[0] * o[0] + o[1] * o[1]) + (o[2] * o[2] + o[3] * o[3]);
;                             u32x2 w; w.x = cvt_pk_bf16(o[0], o[1]); w.y = cvt_pk_bf16(o[2], o[3]); *(u32x2*)(XN + off + bj * HALF + n * 16) = w; }
;                         else *(f32x4*)(out + off + bj * HALF + n * 16) = o;
;                     }
;                 if (NEXT) { ss += __shfl_xor(ss, 16); ss += __shfl_xor(ss, 32); if (fq == 0) atomicAdd(rowss + row, ss); }
;                 if (m & 1) asm volatile("" ::: "memory");
;             }
.LBB0_919:
	v_lshl_add_u32 v136, s74, 8, v138
	v_lshl_or_b32 v134, s62, 8, v140
	v_and_b32_e32 v200, 0xfffffff3, v134
	v_and_b32_e32 v201, 16, v237
	v_or_b32_e32 v200, v200, v201
	v_and_b32_e32 v201, 32, v237
	v_lshrrev_b32_e32 v201, 2, v201
	v_or_b32_e32 v200, v200, v201
	v_lshlrev_b32_e32 v196, 11, v136
	v_lshl_add_u32 v196, v200, 1, v196
	v_readlane_b32 s14, v253, 46
	v_readlane_b32 s15, v253, 47
	v_readlane_b32 s90, v254, 49
	v_readlane_b32 s91, v254, 50
	v_readlane_b32 s89, v254, 58
	v_readlane_b32 s88, v254, 60
	global_load_dwordx4 v[148:151], v196, s[94:95]
	global_load_dwordx4 v[152:155], v196, s[94:95] offset:256
	v_add_u32_e32 v197, 0x8000, v196
	global_load_dwordx4 v[156:159], v197, s[94:95]
	global_load_dwordx4 v[160:163], v197, s[94:95] offset:256
	v_add_u32_e32 v197, 0x10000, v196
	global_load_dwordx4 v[164:167], v197, s[94:95]
	global_load_dwordx4 v[168:171], v197, s[94:95] offset:256
	v_add_u32_e32 v197, 0x18000, v196
	global_load_dwordx4 v[172:175], v197, s[94:95]
	global_load_dwordx4 v[176:179], v197, s[94:95] offset:256
	v_add_u32_e32 v197, 0x40000, v196
	global_load_dwordx4 v[180:183], v197, s[94:95]
	global_load_dwordx4 v[184:187], v197, s[94:95] offset:256
	v_add_u32_e32 v197, 0x48000, v196
	global_load_dwordx4 v[188:191], v197, s[94:95]
	global_load_dwordx4 v[192:195], v197, s[94:95] offset:256
	v_and_b32_e32 v201, 64, v237
	v_xor_b32_e32 v200, 16, v237
	v_add_u32_e32 v201, 64, v201
	v_cmp_lt_i32_e32 vcc, v200, v201
	s_nop 1
	v_cndmask_b32_e32 v200, v237, v200, vcc
	v_lshlrev_b32_e32 v146, 2, v200
	v_xor_b32_e32 v200, 32, v237
	v_cmp_lt_i32_e32 vcc, v200, v201
	s_nop 1
	v_cndmask_b32_e32 v200, v237, v200, vcc
	v_lshlrev_b32_e32 v147, 2, v200
	s_waitcnt vmcnt(10)
	v_permlane16_swap_b32_e32 v148, v150
	v_permlane16_swap_b32_e32 v149, v151
	v_lshlrev_b32_e32 v200, 16, v148
	v_and_b32_e32 v201, 0xffff0000, v148
	v_lshlrev_b32_e32 v148, 16, v149
	v_and_b32_e32 v149, 0xffff0000, v149
	v_pk_add_f32 v[124:125], v[124:125], v[200:201]
	v_pk_add_f32 v[126:127], v[126:127], v[148:149]
	v_mul_f32_e32 v198, v124, v124
	v_fmac_f32_e32 v198, v125, v125
	v_fmac_f32_e32 v198, v126, v126
	v_fmac_f32_e32 v198, v127, v127
	v_lshlrev_b32_e32 v200, 16, v150
	v_and_b32_e32 v201, 0xffff0000, v150
	v_lshlrev_b32_e32 v150, 16, v151
	v_and_b32_e32 v151, 0xffff0000, v151
	v_pk_add_f32 v[120:121], v[120:121], v[200:201]
	v_pk_add_f32 v[122:123], v[122:123], v[150:151]
	v_fmac_f32_e32 v198, v120, v120
	v_fmac_f32_e32 v198, v121, v121
	v_fmac_f32_e32 v198, v122, v122
	v_fmac_f32_e32 v198, v123, v123
	v_cvt_pk_bf16_f32 v124, v124, v125
	v_cvt_pk_bf16_f32 v125, v126, v127
	v_cvt_pk_bf16_f32 v126, v120, v121
	v_cvt_pk_bf16_f32 v127, v122, v123
	s_nop 1
	v_permlane16_swap_b32_e32 v124, v126
	v_permlane16_swap_b32_e32 v125, v127
	v_permlane16_swap_b32_e32 v152, v154
	v_permlane16_swap_b32_e32 v153, v155
	v_lshlrev_b32_e32 v200, 16, v152
	v_and_b32_e32 v201, 0xffff0000, v152
	v_lshlrev_b32_e32 v152, 16, v153
	v_and_b32_e32 v153, 0xffff0000, v153
	v_pk_add_f32 v[116:117], v[116:117], v[200:201]
	v_pk_add_f32 v[118:119], v[118:119], v[152:153]
	v_fmac_f32_e32 v198, v116, v116
	v_fmac_f32_e32 v198, v117, v117
	v_fmac_f32_e32 v198, v118, v118
	v_fmac_f32_e32 v198, v119, v119
	v_lshlrev_b32_e32 v200, 16, v154
	v_and_b32_e32 v201, 0xffff0000, v154
	v_lshlrev_b32_e32 v154, 16, v155
	v_and_b32_e32 v155, 0xffff0000, v155
	v_pk_add_f32 v[112:113], v[112:113], v[200:201]
	v_pk_add_f32 v[114:115], v[114:115], v[154:155]
	v_fmac_f32_e32 v198, v112, v112
	v_fmac_f32_e32 v198, v113, v113
	v_fmac_f32_e32 v198, v114, v114
	v_fmac_f32_e32 v198, v115, v115
	v_cvt_pk_bf16_f32 v116, v116, v117
	v_cvt_pk_bf16_f32 v117, v118, v119
	v_cvt_pk_bf16_f32 v118, v112, v113
	v_cvt_pk_bf16_f32 v119, v114, v115
	s_nop 1
	v_permlane16_swap_b32_e32 v116, v118
	v_permlane16_swap_b32_e32 v117, v119
	global_store_dwordx4 v196, v[124:127], s[94:95]
	global_store_dwordx4 v196, v[116:119], s[94:95] offset:256
	ds_bpermute_b32 v199, v146, v198
	s_waitcnt lgkmcnt(0)
	v_add_f32_e32 v198, v198, v199
	ds_bpermute_b32 v199, v147, v198
	v_lshlrev_b32_e32 v197, 2, v136
	s_waitcnt lgkmcnt(0)
	v_add_f32_e32 v198, v198, v199
	s_and_saveexec_b64 s[2:3], s[0:1]
	s_cbranch_execz .Lmy_er_skip0
	global_atomic_add_f32 v197, v198, s[14:15]
.Lmy_er_skip0:
	s_or_b64 exec, exec, s[2:3]
	s_waitcnt vmcnt(11)
	v_permlane16_swap_b32_e32 v156, v158
	v_permlane16_swap_b32_e32 v157, v159
	v_lshlrev_b32_e32 v200, 16, v156
	v_and_b32_e32 v201, 0xffff0000, v156
	v_lshlrev_b32_e32 v156, 16, v157
	v_and_b32_e32 v157, 0xffff0000, v157
	v_pk_add_f32 v[108:109], v[108:109], v[200:201]
	v_pk_add_f32 v[110:111], v[110:111], v[156:157]
	v_mul_f32_e32 v198, v108, v108
	v_fmac_f32_e32 v198, v109, v109
	v_fmac_f32_e32 v198, v110, v110
	v_fmac_f32_e32 v198, v111, v111
	v_lshlrev_b32_e32 v200, 16, v158
	v_and_b32_e32 v201, 0xffff0000, v158
	v_lshlrev_b32_e32 v158, 16, v159
	v_and_b32_e32 v159, 0xffff0000, v159
	v_pk_add_f32 v[104:105], v[104:105], v[200:201]
	v_pk_add_f32 v[106:107], v[106:107], v[158:159]
	v_fmac_f32_e32 v198, v104, v104
	v_fmac_f32_e32 v198, v105, v105
	v_fmac_f32_e32 v198, v106, v106
	v_fmac_f32_e32 v198, v107, v107
	v_cvt_pk_bf16_f32 v108, v108, v109
	v_cvt_pk_bf16_f32 v109, v110, v111
	v_cvt_pk_bf16_f32 v110, v104, v105
	v_cvt_pk_bf16_f32 v111, v106, v107
	s_nop 1
	v_permlane16_swap_b32_e32 v108, v110
	v_permlane16_swap_b32_e32 v109, v111
	v_permlane16_swap_b32_e32 v160, v162
	v_permlane16_swap_b32_e32 v161, v163
	v_lshlrev_b32_e32 v200, 16, v160
	v_and_b32_e32 v201, 0xffff0000, v160
	v_lshlrev_b32_e32 v160, 16, v161
	v_and_b32_e32 v161, 0xffff0000, v161
	v_pk_add_f32 v[100:101], v[100:101], v[200:201]
	v_pk_add_f32 v[102:103], v[102:103], v[160:161]
	v_fmac_f32_e32 v198, v100, v100
	v_fmac_f32_e32 v198, v101, v101
	v_fmac_f32_e32 v198, v102, v102
	v_fmac_f32_e32 v198, v103, v103
	v_lshlrev_b32_e32 v200, 16, v162
	v_and_b32_e32 v201, 0xffff0000, v162
	v_lshlrev_b32_e32 v162, 16, v163
	v_and_b32_e32 v163, 0xffff0000, v163
	v_pk_add_f32 v[96:97], v[96:97], v[200:201]
	v_pk_add_f32 v[98:99], v[98:99], v[162:163]
	v_fmac_f32_e32 v198, v96, v96
	v_fmac_f32_e32 v198, v97, v97
	v_fmac_f32_e32 v198, v98, v98
	v_fmac_f32_e32 v198, v99, v99
	v_cvt_pk_bf16_f32 v100, v100, v101
	v_cvt_pk_bf16_f32 v101, v102, v103
	v_cvt_pk_bf16_f32 v102, v96, v97
	v_cvt_pk_bf16_f32 v103, v98, v99
	s_nop 1
	v_permlane16_swap_b32_e32 v100, v102
	v_permlane16_swap_b32_e32 v101, v103
	v_add_u32_e32 v197, 0x8000, v196
	global_store_dwordx4 v197, v[108:111], s[94:95]
	global_store_dwordx4 v197, v[100:103], s[94:95] offset:256
	ds_bpermute_b32 v199, v146, v198
	s_waitcnt lgkmcnt(0)
	v_add_f32_e32 v198, v198, v199
	ds_bpermute_b32 v199, v147, v198
	v_or_b32_e32 v197, 16, v136
	v_lshlrev_b32_e32 v197, 2, v197
	s_waitcnt lgkmcnt(0)
	v_add_f32_e32 v198, v198, v199
	s_and_saveexec_b64 s[2:3], s[0:1]
	s_cbranch_execz .Lmy_er_skip1
	global_atomic_add_f32 v197, v198, s[14:15]
; __device__ __forceinline__ unsigned cvt_pk_bf16(float lo, float hi) { unsigned r; asm volatile("v_cvt_pk_bf16_f32 %0, %1, %2" : "=v"(r) : "v"(lo), "v"(hi)); return r; }
;     __device__ __forceinline__ void operator()(const f32x4 (&acc)[2][2][4][2], const Unit& u, int wr, int wc, int fr, int fq) const {
;         typedef unsigned u32x2 __attribute__((ext_vector_type(2)));
;         const int col0 = u.pn * BM + wc * 32 + 4 * fq;
; #pragma unroll
;         for (int ai = 0; ai < 2; ++ai)
; #pragma unroll
;             for (int m = 0; m < 4; ++m) {
;                 const int row = u.pm * BM + ai * HALF + wr * 64 + m * 16 + fr;
;                 const size_t off = (size_t)row * 1024 + col0;
;                 float ss = 0.f;
; #pragma unroll
;                 for (int bj = 0; bj < 2; ++bj)
; #pragma unroll
;                     for (int n = 0; n < 2; ++n) {
;                         f32x4 bs;
;                         { const u32x2 hb = *(const u32x2*)(baseh + off + bj * HALF + n * 16); bs = (f32x4){__uint_as_float(hb.x << 16), __uint_as_float(hb.x & 0xffff0000u), __uint_as_float(hb.y << 16), __uint_as_float(hb.y & 0xffff0000u)}; }
;                         const f32x4 o = bs + acc[ai][bj][m][n];
;                         if (NEXT) { ss += (o[0] * o[0] + o[1] * o[1]) + (o[2] * o[2] + o[3] * o[3]);
;                             u32x2 w; w.x = cvt_pk_bf16(o[0], o[1]); w.y = cvt_pk_bf16(o[2], o[3]); *(u32x2*)(XN + off + bj * HALF + n * 16) = w; }
;                         else *(f32x4*)(out + off + bj * HALF + n * 16) = o;
;                     }
;                 if (NEXT) { ss += __shfl_xor(ss, 16); ss += __shfl_xor(ss, 32); if (fq == 0) atomicAdd(rowss + row, ss); }
;                 if (m & 1) asm volatile("" ::: "memory");
;             }
.Lmy_er_skip1:
	s_or_b64 exec, exec, s[2:3]
	v_add_u32_e32 v197, 0x50000, v196
	global_load_dwordx4 v[120:123], v197, s[94:95]
	global_load_dwordx4 v[112:115], v197, s[94:95] offset:256
	v_add_u32_e32 v197, 0x58000, v196
	global_load_dwordx4 v[104:107], v197, s[94:95]
	global_load_dwordx4 v[96:99], v197, s[94:95] offset:256
	s_waitcnt vmcnt(16)
	v_permlane16_swap_b32_e32 v164, v166
	v_permlane16_swap_b32_e32 v165, v167
	v_lshlrev_b32_e32 v200, 16, v164
	v_and_b32_e32 v201, 0xffff0000, v164
	v_lshlrev_b32_e32 v164, 16, v165
	v_and_b32_e32 v165, 0xffff0000, v165
	v_pk_add_f32 v[92:93], v[92:93], v[200:201]
	v_pk_add_f32 v[94:95], v[94:95], v[164:165]
	v_mul_f32_e32 v198, v92, v92
	v_fmac_f32_e32 v198, v93, v93
	v_fmac_f32_e32 v198, v94, v94
	v_fmac_f32_e32 v198, v95, v95
	v_lshlrev_b32_e32 v200, 16, v166
	v_and_b32_e32 v201, 0xffff0000, v166
	v_lshlrev_b32_e32 v166, 16, v167
	v_and_b32_e32 v167, 0xffff0000, v167
	v_pk_add_f32 v[88:89], v[88:89], v[200:201]
	v_pk_add_f32 v[90:91], v[90:91], v[166:167]
	v_fmac_f32_e32 v198, v88, v88
	v_fmac_f32_e32 v198, v89, v89
	v_fmac_f32_e32 v198, v90, v90
	v_fmac_f32_e32 v198, v91, v91
	v_cvt_pk_bf16_f32 v92, v92, v93
	v_cvt_pk_bf16_f32 v93, v94, v95
	v_cvt_pk_bf16_f32 v94, v88, v89
	v_cvt_pk_bf16_f32 v95, v90, v91
	s_nop 1
	v_permlane16_swap_b32_e32 v92, v94
	v_permlane16_swap_b32_e32 v93, v95
	v_permlane16_swap_b32_e32 v168, v170
	v_permlane16_swap_b32_e32 v169, v171
	v_lshlrev_b32_e32 v200, 16, v168
	v_and_b32_e32 v201, 0xffff0000, v168
	v_lshlrev_b32_e32 v168, 16, v169
	v_and_b32_e32 v169, 0xffff0000, v169
	v_pk_add_f32 v[84:85], v[84:85], v[200:201]
	v_pk_add_f32 v[86:87], v[86:87], v[168:169]
	v_fmac_f32_e32 v198, v84, v84
	v_fmac_f32_e32 v198, v85, v85
	v_fmac_f32_e32 v198, v86, v86
	v_fmac_f32_e32 v198, v87, v87
	v_lshlrev_b32_e32 v200, 16, v170
	v_and_b32_e32 v201, 0xffff0000, v170
	v_lshlrev_b32_e32 v170, 16, v171
	v_and_b32_e32 v171, 0xffff0000, v171
	v_pk_add_f32 v[80:81], v[80:81], v[200:201]
	v_pk_add_f32 v[82:83], v[82:83], v[170:171]
	v_fmac_f32_e32 v198, v80, v80
	v_fmac_f32_e32 v198, v81, v81
	v_fmac_f32_e32 v198, v82, v82
	v_fmac_f32_e32 v198, v83, v83
	v_cvt_pk_bf16_f32 v84, v84, v85
	v_cvt_pk_bf16_f32 v85, v86, v87
	v_cvt_pk_bf16_f32 v86, v80, v81
	v_cvt_pk_bf16_f32 v87, v82, v83
	s_nop 1
	v_permlane16_swap_b32_e32 v84, v86
	v_permlane16_swap_b32_e32 v85, v87
	v_add_u32_e32 v197, 0x10000, v196
	global_store_dwordx4 v197, v[92:95], s[94:95]
	global_store_dwordx4 v197, v[84:87], s[94:95] offset:256
	ds_bpermute_b32 v199, v146, v198
	s_waitcnt lgkmcnt(0)
	v_add_f32_e32 v198, v198, v199
	ds_bpermute_b32 v199, v147, v198
	v_or_b32_e32 v197, 32, v136
	v_lshlrev_b32_e32 v197, 2, v197
	s_waitcnt lgkmcnt(0)
	v_add_f32_e32 v198, v198, v199
	s_and_saveexec_b64 s[2:3], s[0:1]
	s_cbranch_execz .Lmy_er_skip2
	global_atomic_add_f32 v197, v198, s[14:15]
.Lmy_er_skip2:
	s_or_b64 exec, exec, s[2:3]
	s_waitcnt vmcnt(17)
	v_permlane16_swap_b32_e32 v172, v174
	v_permlane16_swap_b32_e32 v173, v175
	v_lshlrev_b32_e32 v200, 16, v172
	v_and_b32_e32 v201, 0xffff0000, v172
	v_lshlrev_b32_e32 v172, 16, v173
	v_and_b32_e32 v173, 0xffff0000, v173
	v_pk_add_f32 v[76:77], v[76:77], v[200:201]
	v_pk_add_f32 v[78:79], v[78:79], v[172:173]
	v_mul_f32_e32 v198, v76, v76
	v_fmac_f32_e32 v198, v77, v77
	v_fmac_f32_e32 v198, v78, v78
	v_fmac_f32_e32 v198, v79, v79
	v_lshlrev_b32_e32 v200, 16, v174
	v_and_b32_e32 v201, 0xffff0000, v174
	v_lshlrev_b32_e32 v174, 16, v175
	v_and_b32_e32 v175, 0xffff0000, v175
	v_pk_add_f32 v[72:73], v[72:73], v[200:201]
	v_pk_add_f32 v[74:75], v[74:75], v[174:175]
	v_fmac_f32_e32 v198, v72, v72
	v_fmac_f32_e32 v198, v73, v73
	v_fmac_f32_e32 v198, v74, v74
	v_fmac_f32_e32 v198, v75, v75
	v_cvt_pk_bf16_f32 v76, v76, v77
	v_cvt_pk_bf16_f32 v77, v78, v79
	v_cvt_pk_bf16_f32 v78, v72, v73
	v_cvt_pk_bf16_f32 v79, v74, v75
	s_nop 1
	v_permlane16_swap_b32_e32 v76, v78
	v_permlane16_swap_b32_e32 v77, v79
	v_permlane16_swap_b32_e32 v176, v178
	v_permlane16_swap_b32_e32 v177, v179
	v_lshlrev_b32_e32 v200, 16, v176
	v_and_b32_e32 v201, 0xffff0000, v176
	v_lshlrev_b32_e32 v176, 16, v177
	v_and_b32_e32 v177, 0xffff0000, v177
	v_pk_add_f32 v[68:69], v[68:69], v[200:201]
	v_pk_add_f32 v[70:71], v[70:71], v[176:177]
	v_fmac_f32_e32 v198, v68, v68
	v_fmac_f32_e32 v198, v69, v69
	v_fmac_f32_e32 v198, v70, v70
	v_fmac_f32_e32 v198, v71, v71
	v_lshlrev_b32_e32 v200, 16, v178
	v_and_b32_e32 v201, 0xffff0000, v178
	v_lshlrev_b32_e32 v178, 16, v179
	v_and_b32_e32 v179, 0xffff0000, v179
	v_pk_add_f32 v[64:65], v[64:65], v[200:201]
	v_pk_add_f32 v[66:67], v[66:67], v[178:179]
	v_fmac_f32_e32 v198, v64, v64
	v_fmac_f32_e32 v198, v65, v65
	v_fmac_f32_e32 v198, v66, v66
	v_fmac_f32_e32 v198, v67, v67
	v_cvt_pk_bf16_f32 v68, v68, v69
	v_cvt_pk_bf16_f32 v69, v70, v71
	v_cvt_pk_bf16_f32 v70, v64, v65
	v_cvt_pk_bf16_f32 v71, v66, v67
	s_nop 1
	v_permlane16_swap_b32_e32 v68, v70
	v_permlane16_swap_b32_e32 v69, v71
	v_add_u32_e32 v197, 0x18000, v196
	global_store_dwordx4 v197, v[76:79], s[94:95]
	global_store_dwordx4 v197, v[68:71], s[94:95] offset:256
	ds_bpermute_b32 v199, v146, v198
	s_waitcnt lgkmcnt(0)
	v_add_f32_e32 v198, v198, v199
	ds_bpermute_b32 v199, v147, v198
	v_or_b32_e32 v197, 48, v136
	v_lshlrev_b32_e32 v197, 2, v197
	s_waitcnt lgkmcnt(0)
	v_add_f32_e32 v198, v198, v199
	s_and_saveexec_b64 s[2:3], s[0:1]
	s_cbranch_execz .Lmy_er_skip3
	global_atomic_add_f32 v197, v198, s[14:15]
; __device__ __forceinline__ unsigned cvt_pk_bf16(float lo, float hi) { unsigned r; asm volatile("v_cvt_pk_bf16_f32 %0, %1, %2" : "=v"(r) : "v"(lo), "v"(hi)); return r; }
;     __device__ __forceinline__ void operator()(const f32x4 (&acc)[2][2][4][2], const Unit& u, int wr, int wc, int fr, int fq) const {
;         typedef unsigned u32x2 __attribute__((ext_vector_type(2)));
;         const int col0 = u.pn * BM + wc * 32 + 4 * fq;
; #pragma unroll
;         for (int ai = 0; ai < 2; ++ai)
; #pragma unroll
;             for (int m = 0; m < 4; ++m) {
;                 const int row = u.pm * BM + ai * HALF + wr * 64 + m * 16 + fr;
;                 const size_t off = (size_t)row * 1024 + col0;
;                 float ss = 0.f;
; #pragma unroll
;                 for (int bj = 0; bj < 2; ++bj)
; #pragma unroll
;                     for (int n = 0; n < 2; ++n) {
;                         f32x4 bs;
;                         { const u32x2 hb = *(const u32x2*)(baseh + off + bj * HALF + n * 16); bs = (f32x4){__uint_as_float(hb.x << 16), __uint_as_float(hb.x & 0xffff0000u), __uint_as_float(hb.y << 16), __uint_as_float(hb.y & 0xffff0000u)}; }
;                         const f32x4 o = bs + acc[ai][bj][m][n];
;                         if (NEXT) { ss += (o[0] * o[0] + o[1] * o[1]) + (o[2] * o[2] + o[3] * o[3]);
;                             u32x2 w; w.x = cvt_pk_bf16(o[0], o[1]); w.y = cvt_pk_bf16(o[2], o[3]); *(u32x2*)(XN + off + bj * HALF + n * 16) = w; }
;                         else *(f32x4*)(out + off + bj * HALF + n * 16) = o;
;                     }
;                 if (NEXT) { ss += __shfl_xor(ss, 16); ss += __shfl_xor(ss, 32); if (fq == 0) atomicAdd(rowss + row, ss); }
;                 if (m & 1) asm volatile("" ::: "memory");
;             }
.Lmy_er_skip3:
	s_or_b64 exec, exec, s[2:3]
	s_waitcnt vmcnt(18)
	v_permlane16_swap_b32_e32 v180, v182
	v_permlane16_swap_b32_e32 v181, v183
	v_lshlrev_b32_e32 v200, 16, v180
	v_and_b32_e32 v201, 0xffff0000, v180
	v_lshlrev_b32_e32 v180, 16, v181
	v_and_b32_e32 v181, 0xffff0000, v181
	v_pk_add_f32 v[60:61], v[60:61], v[200:201]
	v_pk_add_f32 v[62:63], v[62:63], v[180:181]
	v_mul_f32_e32 v198, v60, v60
	v_fmac_f32_e32 v198, v61, v61
	v_fmac_f32_e32 v198, v62, v62
	v_fmac_f32_e32 v198, v63, v63
	v_lshlrev_b32_e32 v200, 16, v182
	v_and_b32_e32 v201, 0xffff0000, v182
	v_lshlrev_b32_e32 v182, 16, v183
	v_and_b32_e32 v183, 0xffff0000, v183
	v_pk_add_f32 v[56:57], v[56:57], v[200:201]
	v_pk_add_f32 v[58:59], v[58:59], v[182:183]
	v_fmac_f32_e32 v198, v56, v56
	v_fmac_f32_e32 v198, v57, v57
	v_fmac_f32_e32 v198, v58, v58
	v_fmac_f32_e32 v198, v59, v59
	v_cvt_pk_bf16_f32 v60, v60, v61
	v_cvt_pk_bf16_f32 v61, v62, v63
	v_cvt_pk_bf16_f32 v62, v56, v57
	v_cvt_pk_bf16_f32 v63, v58, v59
	s_nop 1
	v_permlane16_swap_b32_e32 v60, v62
	v_permlane16_swap_b32_e32 v61, v63
	v_permlane16_swap_b32_e32 v184, v186
	v_permlane16_swap_b32_e32 v185, v187
	v_lshlrev_b32_e32 v200, 16, v184
	v_and_b32_e32 v201, 0xffff0000, v184
	v_lshlrev_b32_e32 v184, 16, v185
	v_and_b32_e32 v185, 0xffff0000, v185
	v_pk_add_f32 v[52:53], v[52:53], v[200:201]
	v_pk_add_f32 v[54:55], v[54:55], v[184:185]
	v_fmac_f32_e32 v198, v52, v52
	v_fmac_f32_e32 v198, v53, v53
	v_fmac_f32_e32 v198, v54, v54
	v_fmac_f32_e32 v198, v55, v55
	v_lshlrev_b32_e32 v200, 16, v186
	v_and_b32_e32 v201, 0xffff0000, v186
	v_lshlrev_b32_e32 v186, 16, v187
	v_and_b32_e32 v187, 0xffff0000, v187
	v_pk_add_f32 v[48:49], v[48:49], v[200:201]
	v_pk_add_f32 v[50:51], v[50:51], v[186:187]
	v_fmac_f32_e32 v198, v48, v48
	v_fmac_f32_e32 v198, v49, v49
	v_fmac_f32_e32 v198, v50, v50
	v_fmac_f32_e32 v198, v51, v51
	v_cvt_pk_bf16_f32 v52, v52, v53
	v_cvt_pk_bf16_f32 v53, v54, v55
	v_cvt_pk_bf16_f32 v54, v48, v49
	v_cvt_pk_bf16_f32 v55, v50, v51
	s_nop 1
	v_permlane16_swap_b32_e32 v52, v54
	v_permlane16_swap_b32_e32 v53, v55
	v_add_u32_e32 v197, 0x40000, v196
	global_store_dwordx4 v197, v[60:63], s[94:95]
	global_store_dwordx4 v197, v[52:55], s[94:95] offset:256
	ds_bpermute_b32 v199, v146, v198
	s_waitcnt lgkmcnt(0)
	v_add_f32_e32 v198, v198, v199
	ds_bpermute_b32 v199, v147, v198
	v_or_b32_e32 v197, 0x80, v136
	v_lshlrev_b32_e32 v197, 2, v197
	s_waitcnt lgkmcnt(0)
	v_add_f32_e32 v198, v198, v199
	s_and_saveexec_b64 s[2:3], s[0:1]
	s_cbranch_execz .Lmy_er_skip4
	global_atomic_add_f32 v197, v198, s[14:15]
.Lmy_er_skip4:
	s_or_b64 exec, exec, s[2:3]
	s_waitcnt vmcnt(19)
	v_permlane16_swap_b32_e32 v188, v190
	v_permlane16_swap_b32_e32 v189, v191
	v_lshlrev_b32_e32 v200, 16, v188
	v_and_b32_e32 v201, 0xffff0000, v188
	v_lshlrev_b32_e32 v188, 16, v189
	v_and_b32_e32 v189, 0xffff0000, v189
	v_pk_add_f32 v[44:45], v[44:45], v[200:201]
	v_pk_add_f32 v[46:47], v[46:47], v[188:189]
	v_mul_f32_e32 v198, v44, v44
	v_fmac_f32_e32 v198, v45, v45
	v_fmac_f32_e32 v198, v46, v46
	v_fmac_f32_e32 v198, v47, v47
	v_lshlrev_b32_e32 v200, 16, v190
	v_and_b32_e32 v201, 0xffff0000, v190
	v_lshlrev_b32_e32 v190, 16, v191
	v_and_b32_e32 v191, 0xffff0000, v191
	v_pk_add_f32 v[40:41], v[40:41], v[200:201]
	v_pk_add_f32 v[42:43], v[42:43], v[190:191]
	v_fmac_f32_e32 v198, v40, v40
	v_fmac_f32_e32 v198, v41, v41
	v_fmac_f32_e32 v198, v42, v42
	v_fmac_f32_e32 v198, v43, v43
	v_cvt_pk_bf16_f32 v44, v44, v45
	v_cvt_pk_bf16_f32 v45, v46, v47
	v_cvt_pk_bf16_f32 v46, v40, v41
	v_cvt_pk_bf16_f32 v47, v42, v43
	s_nop 1
	v_permlane16_swap_b32_e32 v44, v46
	v_permlane16_swap_b32_e32 v45, v47
	v_permlane16_swap_b32_e32 v192, v194
	v_permlane16_swap_b32_e32 v193, v195
	v_lshlrev_b32_e32 v200, 16, v192
	v_and_b32_e32 v201, 0xffff0000, v192
	v_lshlrev_b32_e32 v192, 16, v193
	v_and_b32_e32 v193, 0xffff0000, v193
	v_pk_add_f32 v[36:37], v[36:37], v[200:201]
	v_pk_add_f32 v[38:39], v[38:39], v[192:193]
	v_fmac_f32_e32 v198, v36, v36
	v_fmac_f32_e32 v198, v37, v37
	v_fmac_f32_e32 v198, v38, v38
	v_fmac_f32_e32 v198, v39, v39
	v_lshlrev_b32_e32 v200, 16, v194
	v_and_b32_e32 v201, 0xffff0000, v194
	v_lshlrev_b32_e32 v194, 16, v195
	v_and_b32_e32 v195, 0xffff0000, v195
	v_pk_add_f32 v[32:33], v[32:33], v[200:201]
	v_pk_add_f32 v[34:35], v[34:35], v[194:195]
	v_fmac_f32_e32 v198, v32, v32
	v_fmac_f32_e32 v198, v33, v33
	v_fmac_f32_e32 v198, v34, v34
	v_fmac_f32_e32 v198, v35, v35
	v_cvt_pk_bf16_f32 v36, v36, v37
	v_cvt_pk_bf16_f32 v37, v38, v39
	v_cvt_pk_bf16_f32 v38, v32, v33
	v_cvt_pk_bf16_f32 v39, v34, v35
	s_nop 1
	v_permlane16_swap_b32_e32 v36, v38
	v_permlane16_swap_b32_e32 v37, v39
	v_add_u32_e32 v197, 0x48000, v196
	global_store_dwordx4 v197, v[44:47], s[94:95]
	global_store_dwordx4 v197, v[36:39], s[94:95] offset:256
	ds_bpermute_b32 v199, v146, v198
	s_waitcnt lgkmcnt(0)
	v_add_f32_e32 v198, v198, v199
	ds_bpermute_b32 v199, v147, v198
	v_or_b32_e32 v197, 0x90, v136
	v_lshlrev_b32_e32 v197, 2, v197
	s_waitcnt lgkmcnt(0)
	v_add_f32_e32 v198, v198, v199
	s_and_saveexec_b64 s[2:3], s[0:1]
	s_cbranch_execz .Lmy_er_skip5
	global_atomic_add_f32 v197, v198, s[14:15]
; __device__ __forceinline__ unsigned cvt_pk_bf16(float lo, float hi) { unsigned r; asm volatile("v_cvt_pk_bf16_f32 %0, %1, %2" : "=v"(r) : "v"(lo), "v"(hi)); return r; }
;     __device__ __forceinline__ void operator()(const f32x4 (&acc)[2][2][4][2], const Unit& u, int wr, int wc, int fr, int fq) const {
;         typedef unsigned u32x2 __attribute__((ext_vector_type(2)));
;         const int col0 = u.pn * BM + wc * 32 + 4 * fq;
; #pragma unroll
;         for (int ai = 0; ai < 2; ++ai)
; #pragma unroll
;             for (int m = 0; m < 4; ++m) {
;                 const int row = u.pm * BM + ai * HALF + wr * 64 + m * 16 + fr;
;                 const size_t off = (size_t)row * 1024 + col0;
;                 float ss = 0.f;
; #pragma unroll
;                 for (int bj = 0; bj < 2; ++bj)
; #pragma unroll
;                     for (int n = 0; n < 2; ++n) {
;                         f32x4 bs;
;                         { const u32x2 hb = *(const u32x2*)(baseh + off + bj * HALF + n * 16); bs = (f32x4){__uint_as_float(hb.x << 16), __uint_as_float(hb.x & 0xffff0000u), __uint_as_float(hb.y << 16), __uint_as_float(hb.y & 0xffff0000u)}; }
;                         const f32x4 o = bs + acc[ai][bj][m][n];
;                         if (NEXT) { ss += (o[0] * o[0] + o[1] * o[1]) + (o[2] * o[2] + o[3] * o[3]);
;                             u32x2 w; w.x = cvt_pk_bf16(o[0], o[1]); w.y = cvt_pk_bf16(o[2], o[3]); *(u32x2*)(XN + off + bj * HALF + n * 16) = w; }
;                         else *(f32x4*)(out + off + bj * HALF + n * 16) = o;
;                     }
;                 if (NEXT) { ss += __shfl_xor(ss, 16); ss += __shfl_xor(ss, 32); if (fq == 0) atomicAdd(rowss + row, ss); }
;                 if (m & 1) asm volatile("" ::: "memory");
;             }
.Lmy_er_skip5:
	s_or_b64 exec, exec, s[2:3]
	s_waitcnt vmcnt(14)
	v_permlane16_swap_b32_e32 v120, v122
	v_permlane16_swap_b32_e32 v121, v123
	v_lshlrev_b32_e32 v200, 16, v120
	v_and_b32_e32 v201, 0xffff0000, v120
	v_lshlrev_b32_e32 v120, 16, v121
	v_and_b32_e32 v121, 0xffff0000, v121
	v_pk_add_f32 v[28:29], v[28:29], v[200:201]
	v_pk_add_f32 v[30:31], v[30:31], v[120:121]
	v_mul_f32_e32 v198, v28, v28
	v_fmac_f32_e32 v198, v29, v29
	v_fmac_f32_e32 v198, v30, v30
	v_fmac_f32_e32 v198, v31, v31
	v_lshlrev_b32_e32 v200, 16, v122
	v_and_b32_e32 v201, 0xffff0000, v122
	v_lshlrev_b32_e32 v122, 16, v123
	v_and_b32_e32 v123, 0xffff0000, v123
	v_pk_add_f32 v[24:25], v[24:25], v[200:201]
	v_pk_add_f32 v[26:27], v[26:27], v[122:123]
	v_fmac_f32_e32 v198, v24, v24
	v_fmac_f32_e32 v198, v25, v25
	v_fmac_f32_e32 v198, v26, v26
	v_fmac_f32_e32 v198, v27, v27
	v_cvt_pk_bf16_f32 v28, v28, v29
	v_cvt_pk_bf16_f32 v29, v30, v31
	v_cvt_pk_bf16_f32 v30, v24, v25
	v_cvt_pk_bf16_f32 v31, v26, v27
	s_nop 1
	v_permlane16_swap_b32_e32 v28, v30
	v_permlane16_swap_b32_e32 v29, v31
	v_permlane16_swap_b32_e32 v112, v114
	v_permlane16_swap_b32_e32 v113, v115
	v_lshlrev_b32_e32 v200, 16, v112
	v_and_b32_e32 v201, 0xffff0000, v112
	v_lshlrev_b32_e32 v112, 16, v113
	v_and_b32_e32 v113, 0xffff0000, v113
	v_pk_add_f32 v[20:21], v[20:21], v[200:201]
	v_pk_add_f32 v[22:23], v[22:23], v[112:113]
	v_fmac_f32_e32 v198, v20, v20
	v_fmac_f32_e32 v198, v21, v21
	v_fmac_f32_e32 v198, v22, v22
	v_fmac_f32_e32 v198, v23, v23
	v_lshlrev_b32_e32 v200, 16, v114
	v_and_b32_e32 v201, 0xffff0000, v114
	v_lshlrev_b32_e32 v114, 16, v115
	v_and_b32_e32 v115, 0xffff0000, v115
	v_pk_add_f32 v[16:17], v[16:17], v[200:201]
	v_pk_add_f32 v[18:19], v[18:19], v[114:115]
	v_fmac_f32_e32 v198, v16, v16
	v_fmac_f32_e32 v198, v17, v17
	v_fmac_f32_e32 v198, v18, v18
	v_fmac_f32_e32 v198, v19, v19
	v_cvt_pk_bf16_f32 v20, v20, v21
	v_cvt_pk_bf16_f32 v21, v22, v23
	v_cvt_pk_bf16_f32 v22, v16, v17
	v_cvt_pk_bf16_f32 v23, v18, v19
	s_nop 1
	v_permlane16_swap_b32_e32 v20, v22
	v_permlane16_swap_b32_e32 v21, v23
	v_add_u32_e32 v197, 0x50000, v196
	global_store_dwordx4 v197, v[28:31], s[94:95]
	global_store_dwordx4 v197, v[20:23], s[94:95] offset:256
	ds_bpermute_b32 v199, v146, v198
	s_waitcnt lgkmcnt(0)
	v_add_f32_e32 v198, v198, v199
	ds_bpermute_b32 v199, v147, v198
	v_or_b32_e32 v197, 0xa0, v136
	v_lshlrev_b32_e32 v197, 2, v197
	s_waitcnt lgkmcnt(0)
	v_add_f32_e32 v198, v198, v199
	s_and_saveexec_b64 s[2:3], s[0:1]
	s_cbranch_execz .Lmy_er_skip6
	global_atomic_add_f32 v197, v198, s[14:15]
.Lmy_er_skip6:
	s_or_b64 exec, exec, s[2:3]
	s_waitcnt vmcnt(15)
	v_permlane16_swap_b32_e32 v104, v106
	v_permlane16_swap_b32_e32 v105, v107
	v_lshlrev_b32_e32 v200, 16, v104
	v_and_b32_e32 v201, 0xffff0000, v104
	v_lshlrev_b32_e32 v104, 16, v105
	v_and_b32_e32 v105, 0xffff0000, v105
	v_pk_add_f32 v[12:13], v[12:13], v[200:201]
	v_pk_add_f32 v[14:15], v[14:15], v[104:105]
	v_mul_f32_e32 v198, v12, v12
	v_fmac_f32_e32 v198, v13, v13
	v_fmac_f32_e32 v198, v14, v14
	v_fmac_f32_e32 v198, v15, v15
	v_lshlrev_b32_e32 v200, 16, v106
	v_and_b32_e32 v201, 0xffff0000, v106
	v_lshlrev_b32_e32 v106, 16, v107
	v_and_b32_e32 v107, 0xffff0000, v107
	v_pk_add_f32 v[8:9], v[8:9], v[200:201]
	v_pk_add_f32 v[10:11], v[10:11], v[106:107]
	v_fmac_f32_e32 v198, v8, v8
	v_fmac_f32_e32 v198, v9, v9
	v_fmac_f32_e32 v198, v10, v10
	v_fmac_f32_e32 v198, v11, v11
	v_cvt_pk_bf16_f32 v12, v12, v13
	v_cvt_pk_bf16_f32 v13, v14, v15
	v_cvt_pk_bf16_f32 v14, v8, v9
	v_cvt_pk_bf16_f32 v15, v10, v11
	s_nop 1
	v_permlane16_swap_b32_e32 v12, v14
	v_permlane16_swap_b32_e32 v13, v15
	v_permlane16_swap_b32_e32 v96, v98
	v_permlane16_swap_b32_e32 v97, v99
	v_lshlrev_b32_e32 v200, 16, v96
	v_and_b32_e32 v201, 0xffff0000, v96
	v_lshlrev_b32_e32 v96, 16, v97
	v_and_b32_e32 v97, 0xffff0000, v97
	v_pk_add_f32 v[4:5], v[4:5], v[200:201]
	v_pk_add_f32 v[6:7], v[6:7], v[96:97]
	v_fmac_f32_e32 v198, v4, v4
	v_fmac_f32_e32 v198, v5, v5
	v_fmac_f32_e32 v198, v6, v6
	v_fmac_f32_e32 v198, v7, v7
	v_lshlrev_b32_e32 v200, 16, v98
	v_and_b32_e32 v201, 0xffff0000, v98
	v_lshlrev_b32_e32 v98, 16, v99
	v_and_b32_e32 v99, 0xffff0000, v99
	v_pk_add_f32 v[0:1], v[0:1], v[200:201]
	v_pk_add_f32 v[2:3], v[2:3], v[98:99]
	v_fmac_f32_e32 v198, v0, v0
	v_fmac_f32_e32 v198, v1, v1
	v_fmac_f32_e32 v198, v2, v2
	v_fmac_f32_e32 v198, v3, v3
	v_cvt_pk_bf16_f32 v4, v4, v5
	v_cvt_pk_bf16_f32 v5, v6, v7
	v_cvt_pk_bf16_f32 v6, v0, v1
	v_cvt_pk_bf16_f32 v7, v2, v3
	s_nop 1
	v_permlane16_swap_b32_e32 v4, v6
	v_permlane16_swap_b32_e32 v5, v7
	v_add_u32_e32 v197, 0x58000, v196
	global_store_dwordx4 v197, v[12:15], s[94:95]
	global_store_dwordx4 v197, v[4:7], s[94:95] offset:256
	ds_bpermute_b32 v199, v146, v198
	s_waitcnt lgkmcnt(0)
	v_add_f32_e32 v198, v198, v199
	ds_bpermute_b32 v199, v147, v198
	v_or_b32_e32 v197, 0xb0, v136
	v_lshlrev_b32_e32 v197, 2, v197
	s_waitcnt lgkmcnt(0)
	v_add_f32_e32 v198, v198, v199
	s_and_saveexec_b64 s[2:3], s[0:1]
	s_cbranch_execz .Lmy_er_skip7
	global_atomic_add_f32 v197, v198, s[14:15]
